# adds: attention tile commit waits counted (vmcnt 3/2) when the next tile was requested in the same step; drain at loop exit
# speedup vs baseline: 1.0094x; 1.0037x over previous
.LBB0_635:
	s_cmp_lt_i32 s5, 1
	s_cbranch_scc1 .LBB0_639
	s_cmp_lt_i32 s5, 2
	s_cbranch_scc1 .Lat_strict_a
	s_add_i32 s98, s57, 1
	s_cmp_ge_i32 s98, s34
	s_cbranch_scc0 .Lat_strict_a
	s_waitcnt vmcnt(3)
	ds_write_b128 v147, v[104:107] offset:18688
	s_waitcnt vmcnt(2)
	ds_write_b128 v147, v[108:111] offset:27904
	s_branch .Lat_done_a
.Lat_strict_a:
	s_waitcnt vmcnt(1)
	ds_write_b128 v147, v[104:107] offset:18688
	s_waitcnt vmcnt(0)
	ds_write_b128 v147, v[108:111] offset:27904
.Lat_done_a:
	s_and_saveexec_b64 s[50:51], s[42:43]
	s_cbranch_execz .LBB0_638
	v_mov_b32_e32 v2, s55
	ds_read_b32 v2, v2 offset:4
	v_add_u32_e32 v3, 0, v148
	s_waitcnt lgkmcnt(0)
	v_sub_f32_e32 v2, v146, v2
	v_sub_f32_e32 v2, v2, v139
	v_mul_f32_e32 v2, 0x3fb8aa3b, v2
	ds_write_b32 v3, v2 offset:37120

.LBB0_667:
	s_cmp_lt_i32 s5, 3
	s_cbranch_scc1 .Lat_strict_b
	s_cmp_ge_i32 s57, s34
	s_cbranch_scc0 .Lat_strict_b
	s_waitcnt vmcnt(3)
	ds_write_b128 v147, v[96:99]
	s_waitcnt vmcnt(2)
	ds_write_b128 v147, v[100:103] offset:9216
	s_branch .Lat_done_b

.Lat_done_b:
	s_and_saveexec_b64 s[46:47], s[42:43]
	s_cbranch_execz .LBB0_669
	v_mov_b32_e32 v2, s55
	ds_read_b32 v2, v2
	v_add_u32_e32 v3, 0, v148
	s_waitcnt lgkmcnt(0)
	v_sub_f32_e32 v2, v146, v2
	v_sub_f32_e32 v2, v2, v138
	v_mul_f32_e32 v2, 0x3fb8aa3b, v2
	ds_write_b32 v3, v2 offset:18432

; __device__ __forceinline__ float bflo(unsigned w) { return __uint_as_float(w << 16); }
; __device__ __forceinline__ float bfhi(unsigned w) { return __uint_as_float(w & 0xffff0000u); }
; __device__ __forceinline__ void attn_unit(LAS unsigned char* lds, const bf16_t* Qp, const bf16_t* Kp, const bf16_t* VTp, int vpitch, const float* CLp, const float* BTp, const float* CMp, const float* KNp, ...
;     ...
;     if (active) {
;         const float lt = lrun + __shfl_xor(lrun, 32);
;         const float inv = 1.0f / lt;
;         bf16_t* yrow = Yp + (size_t)(32 * wave + r32) * 1024;
; #pragma unroll
;         for (int g = 0; g < 4; ++g) {
;             { bf16_t* p = yrow + 8 * g + 4 * hi; const u32x2 gt = gte[g][0]; u32x2 w;
;               w.x = pk2(o0[4 * g] * inv * bflo(gt.x), o0[4 * g + 1] * inv * bfhi(gt.x)); w.y = pk2(o0[4 * g + 2] * inv * bflo(gt.y), o0[4 * g + 3] * inv * bfhi(gt.y)); *(u32x2*)p = w; }
;             { bf16_t* p = yrow + 32 + 8 * g + 4 * hi; const u32x2 gt = gte[g][1]; u32x2 w;
;               w.x = pk2(o1[4 * g] * inv * bflo(gt.x), o1[4 * g + 1] * inv * bfhi(gt.x)); w.y = pk2(o1[4 * g + 2] * inv * bflo(gt.y), o1[4 * g + 3] * inv * bfhi(gt.y)); *(u32x2*)p = w; }
;         }
.LBB0_679:
	s_waitcnt vmcnt(0)
	s_andn2_b64 vcc, exec, s[40:41]
	s_cbranch_vccnz .LBB0_681
	ds_bpermute_b32 v0, v140, v164
	v_mov_b32_e32 v113, v1
	s_waitcnt vmcnt(7)
	v_and_b32_e32 v7, 0xffff0000, v128
	v_lshlrev_b32_e32 v8, 16, v129
	v_and_b32_e32 v9, 0xffff0000, v129
	s_waitcnt lgkmcnt(0)
	v_add_f32_e32 v0, v164, v0
	v_div_scale_f32 v2, s[12:13], v0, v0, 1.0
	v_rcp_f32_e32 v3, v2
	s_nop 0
	v_fma_f32 v4, -v2, v3, 1.0
	v_fmac_f32_e32 v3, v4, v3
	v_div_scale_f32 v4, vcc, 1.0, v0, 1.0
	v_mul_f32_e32 v5, v4, v3
	v_fma_f32 v6, -v2, v5, v4
	v_fmac_f32_e32 v5, v6, v3
	v_fma_f32 v2, -v2, v5, v4
	v_div_fmas_f32 v2, v2, v3, v5
	v_div_fixup_f32 v0, v2, v0, 1.0
	v_pk_mul_f32 v[4:5], v[32:33], v[0:1] op_sel_hi:[1,0]
	v_lshlrev_b32_e32 v6, 16, v128
	v_lshlrev_b64 v[2:3], 11, v[112:113]
	v_pk_mul_f32 v[4:5], v[4:5], v[6:7]
	v_pk_mul_f32 v[6:7], v[34:35], v[0:1] op_sel_hi:[1,0]
	v_lshl_add_u64 v[2:3], s[66:67], 0, v[2:3]
	v_pk_mul_f32 v[6:7], v[6:7], v[8:9]
	v_lshl_add_u64 v[2:3], v[130:131], 1, v[2:3]
	v_cvt_pk_bf16_f32 v4, v4, v5
	v_cvt_pk_bf16_f32 v5, v6, v7
	global_store_dwordx2 v[2:3], v[4:5], off
	v_pk_mul_f32 v[4:5], v[16:17], v[0:1] op_sel_hi:[1,0]
	s_waitcnt vmcnt(4)
	v_lshlrev_b32_e32 v6, 16, v126
	v_and_b32_e32 v7, 0xffff0000, v126
	v_pk_mul_f32 v[4:5], v[4:5], v[6:7]
	v_pk_mul_f32 v[6:7], v[18:19], v[0:1] op_sel_hi:[1,0]
	v_lshlrev_b32_e32 v8, 16, v127
	v_and_b32_e32 v9, 0xffff0000, v127
	v_pk_mul_f32 v[6:7], v[6:7], v[8:9]
	v_cvt_pk_bf16_f32 v4, v4, v5
	v_cvt_pk_bf16_f32 v5, v6, v7
	global_store_dwordx2 v[2:3], v[4:5], off offset:64
	v_pk_mul_f32 v[4:5], v[36:37], v[0:1] op_sel_hi:[1,0]
	v_lshlrev_b32_e32 v6, 16, v124
	v_and_b32_e32 v7, 0xffff0000, v124
	v_pk_mul_f32 v[4:5], v[4:5], v[6:7]
	v_pk_mul_f32 v[6:7], v[38:39], v[0:1] op_sel_hi:[1,0]
	v_lshlrev_b32_e32 v8, 16, v125
	v_and_b32_e32 v9, 0xffff0000, v125
	v_pk_mul_f32 v[6:7], v[6:7], v[8:9]
	v_cvt_pk_bf16_f32 v4, v4, v5
	v_cvt_pk_bf16_f32 v5, v6, v7
	global_store_dwordx2 v[2:3], v[4:5], off offset:16
	v_pk_mul_f32 v[4:5], v[20:21], v[0:1] op_sel_hi:[1,0]
	s_waitcnt vmcnt(5)
	v_lshlrev_b32_e32 v6, 16, v122
	v_and_b32_e32 v7, 0xffff0000, v122
	v_pk_mul_f32 v[4:5], v[4:5], v[6:7]
	v_pk_mul_f32 v[6:7], v[22:23], v[0:1] op_sel_hi:[1,0]
	v_lshlrev_b32_e32 v8, 16, v123
	v_and_b32_e32 v9, 0xffff0000, v123
	v_pk_mul_f32 v[6:7], v[6:7], v[8:9]
	v_cvt_pk_bf16_f32 v4, v4, v5
	v_cvt_pk_bf16_f32 v5, v6, v7
	global_store_dwordx2 v[2:3], v[4:5], off offset:80
	v_pk_mul_f32 v[4:5], v[40:41], v[0:1] op_sel_hi:[1,0]
	v_lshlrev_b32_e32 v6, 16, v120
	v_and_b32_e32 v7, 0xffff0000, v120
	v_pk_mul_f32 v[4:5], v[4:5], v[6:7]
	v_pk_mul_f32 v[6:7], v[42:43], v[0:1] op_sel_hi:[1,0]
	v_lshlrev_b32_e32 v8, 16, v121
	v_and_b32_e32 v9, 0xffff0000, v121
	v_pk_mul_f32 v[6:7], v[6:7], v[8:9]
	v_cvt_pk_bf16_f32 v4, v4, v5
	v_cvt_pk_bf16_f32 v5, v6, v7
	global_store_dwordx2 v[2:3], v[4:5], off offset:32
	v_pk_mul_f32 v[4:5], v[24:25], v[0:1] op_sel_hi:[1,0]
	s_waitcnt vmcnt(6)
	v_lshlrev_b32_e32 v6, 16, v118
	v_and_b32_e32 v7, 0xffff0000, v118
	v_pk_mul_f32 v[4:5], v[4:5], v[6:7]
	v_pk_mul_f32 v[6:7], v[26:27], v[0:1] op_sel_hi:[1,0]
	v_lshlrev_b32_e32 v8, 16, v119
	v_and_b32_e32 v9, 0xffff0000, v119
	v_pk_mul_f32 v[6:7], v[6:7], v[8:9]
	v_cvt_pk_bf16_f32 v4, v4, v5
	v_cvt_pk_bf16_f32 v5, v6, v7
	global_store_dwordx2 v[2:3], v[4:5], off offset:96
	v_pk_mul_f32 v[4:5], v[44:45], v[0:1] op_sel_hi:[1,0]
	v_lshlrev_b32_e32 v6, 16, v116
	v_and_b32_e32 v7, 0xffff0000, v116
	v_pk_mul_f32 v[4:5], v[4:5], v[6:7]
	v_pk_mul_f32 v[6:7], v[46:47], v[0:1] op_sel_hi:[1,0]
	v_lshlrev_b32_e32 v8, 16, v117
	v_and_b32_e32 v9, 0xffff0000, v117
	v_pk_mul_f32 v[6:7], v[6:7], v[8:9]
	v_cvt_pk_bf16_f32 v4, v4, v5
	v_cvt_pk_bf16_f32 v5, v6, v7
	global_store_dwordx2 v[2:3], v[4:5], off offset:48
	v_pk_mul_f32 v[4:5], v[28:29], v[0:1] op_sel_hi:[1,0]
	s_waitcnt vmcnt(7)
	v_lshlrev_b32_e32 v6, 16, v114
	v_and_b32_e32 v7, 0xffff0000, v114
	v_pk_mul_f32 v[4:5], v[4:5], v[6:7]
	v_pk_mul_f32 v[6:7], v[30:31], v[0:1] op_sel_hi:[1,0]
	v_lshlrev_b32_e32 v8, 16, v115
	v_and_b32_e32 v9, 0xffff0000, v115
	v_pk_mul_f32 v[6:7], v[6:7], v[8:9]
	v_cvt_pk_bf16_f32 v4, v4, v5
	v_cvt_pk_bf16_f32 v5, v6, v7
	global_store_dwordx2 v[2:3], v[4:5], off offset:112
